# final RMSNorm: both row-statistic fetches and the 8 x loads of an iteration issued together (3 dependent round trips -> 1), same arithmetic
# speedup vs baseline: 1.0192x; 1.0025x over previous
.LBB0_66:
	v_ashrrev_i32_e32 v1, 31, v0
	v_lshlrev_b64 v[20:21], 6, v[0:1]
	s_waitcnt vmcnt(12)
	v_lshl_add_u64 v[32:33], s[12:13], 0, v[20:21]
	global_load_dwordx4 v[20:23], v[32:33], off offset:48
	global_load_dwordx4 v[24:27], v[32:33], off offset:32
	global_load_dwordx4 v[28:31], v[32:33], off offset:16
	s_nop 0
	global_load_dwordx4 v[32:35], v[32:33], off
	v_add_u32_e32 v72, 1, v0
	v_ashrrev_i32_e32 v73, 31, v72
	v_lshlrev_b64 v[72:73], 6, v[72:73]
	v_lshl_add_u64 v[84:85], s[12:13], 0, v[72:73]
	global_load_dwordx4 v[72:75], v[84:85], off offset:48
	global_load_dwordx4 v[76:79], v[84:85], off offset:32
	global_load_dwordx4 v[80:83], v[84:85], off offset:16
	s_nop 0
	global_load_dwordx4 v[84:87], v[84:85], off
	s_mov_b32 s0, 0x3a800000
	v_mov_b32_e32 v53, v3
	v_mov_b32_e32 v55, v3
	v_mov_b32_e32 v57, v3
	v_lshlrev_b64 v[120:121], 12, v[0:1]
	v_lshl_add_u64 v[120:121], s[22:23], 0, v[120:121]
	v_lshl_add_u64 v[136:137], v[120:121], 0, s[10:11]
	v_lshl_add_u64 v[58:59], v[120:121], 0, v[2:3]
	v_lshl_add_u64 v[66:67], v[136:137], 0, v[2:3]
	v_lshl_add_u64 v[62:63], v[136:137], 0, v[52:53]
	v_lshl_add_u64 v[60:61], v[136:137], 0, v[54:55]
	global_load_dwordx4 v[148:151], v[58:59], off
	global_load_dwordx4 v[144:147], v[66:67], off
	global_load_dwordx4 v[140:143], v[58:59], off offset:1024
	global_load_dwordx4 v[132:135], v[62:63], off
	global_load_dwordx4 v[124:127], v[58:59], off offset:2048
	global_load_dwordx4 v[128:131], v[60:61], off
	global_load_dwordx4 v[120:123], v[58:59], off offset:3072
	v_lshl_add_u64 v[64:65], v[136:137], 0, v[56:57]
	global_load_dwordx4 v[136:139], v[64:65], off
	s_waitcnt vmcnt(14)
	v_add_f32_e32 v24, v24, v25
	v_add_f32_e32 v26, v26, v27
	s_waitcnt vmcnt(12)
	v_mov_b32_e32 v36, v33
	v_mov_b32_e32 v37, v34
	v_mov_b32_e32 v33, v35
	v_mov_b32_e32 v34, v29
	v_mov_b32_e32 v35, v30
	v_mov_b32_e32 v29, v31
	v_pk_add_f32 v[32:33], v[36:37], v[32:33]
	v_pk_add_f32 v[28:29], v[34:35], v[28:29]
	v_pk_add_f32 v[32:33], v[32:33], v[32:33] op_sel:[0,1] op_sel_hi:[1,0]
	v_pk_add_f32 v[28:29], v[28:29], v[28:29] op_sel:[0,1] op_sel_hi:[1,0]
	v_mov_b32_e32 v33, v20
	v_mov_b32_e32 v29, v21
	v_mov_b32_e32 v25, v22
	v_mov_b32_e32 v27, v23
	v_pk_add_f32 v[20:21], v[32:33], v[28:29]
	v_pk_add_f32 v[22:23], v[24:25], v[26:27]
	s_nop 0
	v_pk_add_f32 v[36:37], v[20:21], v[22:23]
	s_waitcnt vmcnt(10)
	v_add_f32_e32 v76, v76, v77
	v_add_f32_e32 v78, v78, v79
	s_waitcnt vmcnt(8)
	v_mov_b32_e32 v90, v85
	v_mov_b32_e32 v91, v86
	v_mov_b32_e32 v85, v87
	v_mov_b32_e32 v86, v81
	v_mov_b32_e32 v87, v82
	v_mov_b32_e32 v81, v83
	v_pk_add_f32 v[84:85], v[90:91], v[84:85]
	v_pk_add_f32 v[80:81], v[86:87], v[80:81]
	v_pk_add_f32 v[84:85], v[84:85], v[84:85] op_sel:[0,1] op_sel_hi:[1,0]
	v_pk_add_f32 v[80:81], v[80:81], v[80:81] op_sel:[0,1] op_sel_hi:[1,0]
	v_mov_b32_e32 v85, v72
	v_mov_b32_e32 v81, v73
	v_mov_b32_e32 v77, v74
	v_mov_b32_e32 v79, v75
	v_pk_add_f32 v[72:73], v[84:85], v[80:81]
	v_pk_add_f32 v[74:75], v[76:77], v[78:79]
	s_nop 0
	v_pk_add_f32 v[72:73], v[72:73], v[74:75]
	v_mov_b32_e32 v75, v36
	v_mov_b32_e32 v74, v72
	v_mov_b32_e32 v36, v73
	v_pk_add_f32 v[72:73], v[74:75], v[36:37]
	s_nop 0
	v_pk_fma_f32 v[72:73], v[72:73], s[0:1], v[172:173] op_sel_hi:[1,0,0]
	s_nop 0
	v_mul_f32_e32 v74, 0x4b800000, v73
	v_cmp_gt_f32_e64 s[0:1], s33, v73
	v_cmp_gt_f32_e32 vcc, s33, v72
	s_nop 0
	v_cndmask_b32_e64 v73, v73, v74, s[0:1]
	v_rsq_f32_e32 v68, v73
	v_mul_f32_e32 v73, 0x4b800000, v72
	v_cndmask_b32_e32 v72, v72, v73, vcc
	v_rsq_f32_e32 v70, v72
	v_mul_f32_e32 v69, 0x45800000, v68
	v_cndmask_b32_e64 v68, v68, v69, s[0:1]
	v_mul_f32_e32 v71, 0x45800000, v70
	v_cndmask_b32_e32 v70, v70, v71, vcc
	v_add_u32_e32 v0, s8, v0
	v_cmp_lt_i32_e32 vcc, s63, v0
	s_or_b64 s[6:7], vcc, s[6:7]
	s_waitcnt vmcnt(7)
	v_pk_mul_f32 v[148:149], v[148:149], v[68:69] op_sel_hi:[1,0]
	v_pk_mul_f32 v[150:151], v[150:151], v[68:69] op_sel_hi:[1,0]
	s_waitcnt vmcnt(3)
	v_pk_mul_f32 v[124:125], v[124:125], v[68:69] op_sel_hi:[1,0]
	v_pk_mul_f32 v[126:127], v[126:127], v[68:69] op_sel_hi:[1,0]
	s_waitcnt vmcnt(1)
	v_pk_mul_f32 v[120:121], v[120:121], v[68:69] op_sel_hi:[1,0]
	v_pk_mul_f32 v[122:123], v[122:123], v[68:69] op_sel_hi:[1,0]
	v_pk_mul_f32 v[126:127], v[14:15], v[126:127]
	v_pk_mul_f32 v[124:125], v[12:13], v[124:125]
	v_pk_mul_f32 v[122:123], v[18:19], v[122:123]
	v_pk_mul_f32 v[120:121], v[16:17], v[120:121]
	v_pk_mul_f32 v[144:145], v[144:145], v[70:71] op_sel_hi:[1,0]
	v_pk_mul_f32 v[146:147], v[146:147], v[70:71] op_sel_hi:[1,0]
	v_pk_mul_f32 v[140:141], v[140:141], v[68:69] op_sel_hi:[1,0]
	v_pk_mul_f32 v[142:143], v[142:143], v[68:69] op_sel_hi:[1,0]
	v_pk_mul_f32 v[132:133], v[132:133], v[70:71] op_sel_hi:[1,0]
	v_pk_mul_f32 v[134:135], v[134:135], v[70:71] op_sel_hi:[1,0]
	global_store_dwordx4 v[58:59], v[124:127], off offset:2048
	global_store_dwordx4 v[58:59], v[120:123], off offset:3072
	v_pk_mul_f32 v[150:151], v[6:7], v[150:151]
	v_pk_mul_f32 v[124:125], v[128:129], v[70:71] op_sel_hi:[1,0]
	v_pk_mul_f32 v[126:127], v[130:131], v[70:71] op_sel_hi:[1,0]
	s_waitcnt vmcnt(2)
	v_pk_mul_f32 v[120:121], v[136:137], v[70:71] op_sel_hi:[1,0]
	v_pk_mul_f32 v[122:123], v[138:139], v[70:71] op_sel_hi:[1,0]
	v_pk_mul_f32 v[148:149], v[4:5], v[148:149]
	v_pk_mul_f32 v[146:147], v[6:7], v[146:147]
	v_pk_mul_f32 v[144:145], v[4:5], v[144:145]
	v_pk_mul_f32 v[142:143], v[10:11], v[142:143]
	v_pk_mul_f32 v[140:141], v[8:9], v[140:141]
	v_pk_mul_f32 v[134:135], v[10:11], v[134:135]
	v_pk_mul_f32 v[132:133], v[8:9], v[132:133]
	v_pk_mul_f32 v[126:127], v[14:15], v[126:127]
	v_pk_mul_f32 v[124:125], v[12:13], v[124:125]
	v_pk_mul_f32 v[122:123], v[18:19], v[122:123]
	v_pk_mul_f32 v[120:121], v[16:17], v[120:121]
	global_store_dwordx4 v[58:59], v[148:151], off
	global_store_dwordx4 v[66:67], v[144:147], off
	global_store_dwordx4 v[58:59], v[140:143], off offset:1024
	global_store_dwordx4 v[62:63], v[132:135], off
	global_store_dwordx4 v[60:61], v[124:127], off
	global_store_dwordx4 v[64:65], v[120:123], off
	s_andn2_b64 exec, exec, s[6:7]
	s_cbranch_execnz .LBB0_66
